# v063 plus P1 V^T epilogue rewritten: lane pairs exchange packed bf16 words (DPP + v_perm_b32) so the 128 two-byte stores per lane become 64 dword stores with SGPR-base addressing
# baseline (speedup 1.0000x reference)
; __device__ __forceinline__ unsigned cvt_pk_bf16(float lo, float hi) { return pk_bf16(lo, hi); }
;     __device__ __forceinline__ void operator()(const f32x4 (&acc)[2][2][4][2], const Unit& u, int wr, int wc, int fr, int fq) const {
;     ...
;             EPI_ROWS_BEGIN
;                 const int cc = (pn - 8) * 256 + colt, vh = cc >> 6, d = cc & 63, b = row >> 14, t = row & (SEQ - 1);
;                 bf16_t* dst = vt + ((size_t)(b * 12 + vh) * 64 + d) * VTP + t;
;                 const unsigned w0 = cvt_pk_bf16(v0[0], v0[1]), w1 = cvt_pk_bf16(v0[2], v0[3]), w2 = cvt_pk_bf16(v1[0], v1[1]), w3 = cvt_pk_bf16(v1[2], v1[3]);
;                 dst[0 * (size_t)VTP] = (bf16_t)(w0 & 0xffffu); dst[1 * (size_t)VTP] = (bf16_t)(w0 >> 16);
;                 dst[2 * (size_t)VTP] = (bf16_t)(w1 & 0xffffu); dst[3 * (size_t)VTP] = (bf16_t)(w1 >> 16);
;                 dst[4 * (size_t)VTP] = (bf16_t)(w2 & 0xffffu); dst[5 * (size_t)VTP] = (bf16_t)(w2 >> 16);
;                 dst[6 * (size_t)VTP] = (bf16_t)(w3 & 0xffffu); dst[7 * (size_t)VTP] = (bf16_t)(w3 >> 16);
;             EPI_ROWS_END
.LBB0_303:
	s_andn2_b64 vcc, exec, s[24:25]
	s_cbranch_vccnz .LBB0_305
	s_lshl_b32 s3, s81, 8
	s_add_i32 s3, s68, s3
	s_lshr_b32 s3, s3, 6
	s_ashr_i32 s17, s2, 14
	s_mul_i32 s17, s17, 12
	s_add_i32 s17, s17, s3
	s_lshl_b32 s17, s17, 6
	s_and_b32 s23, s2, 0x3fc0
	v_and_b32_e32 v224, 1, v193
	v_add_u32_e32 v225, s17, v206
	v_add_u32_e32 v225, v225, v224
	v_and_b32_e32 v226, 14, v193
	v_or_b32_e32 v226, s23, v226
	v_lshlrev_b32_e32 v226, 1, v226
	v_mad_u32_u24 v227, v225, s75, v226
	v_mov_b32_e32 v228, 0x1000504
	v_mov_b32_e32 v229, 0x7060302
	v_cmp_eq_u32_e32 vcc, 1, v224
	s_nop 1
	v_cndmask_b32_e32 v228, v228, v229, vcc
	s_add_u32 s24, s10, 0x0
	s_addc_u32 s25, s11, 0
	v_mov_b32_dpp v230, v188 quad_perm:[1,0,3,2] row_mask:0xf bank_mask:0xf
	s_nop 0
	v_perm_b32 v231, v188, v230, v228
	global_store_dword v227, v231, s[24:25] offset:0
	v_mov_b32_dpp v232, v180 quad_perm:[1,0,3,2] row_mask:0xf bank_mask:0xf
	s_nop 0
	v_perm_b32 v233, v180, v232, v228
	global_store_dword v227, v233, s[24:25] offset:32
	v_mov_b32_dpp v234, v172 quad_perm:[1,0,3,2] row_mask:0xf bank_mask:0xf
	s_nop 0
	v_perm_b32 v235, v172, v234, v228
	global_store_dword v227, v235, s[24:25] offset:64
	v_mov_b32_dpp v236, v164 quad_perm:[1,0,3,2] row_mask:0xf bank_mask:0xf
	s_nop 0
	v_perm_b32 v237, v164, v236, v228
	global_store_dword v227, v237, s[24:25] offset:96
	v_mov_b32_dpp v230, v156 quad_perm:[1,0,3,2] row_mask:0xf bank_mask:0xf
	s_nop 0
	v_perm_b32 v231, v156, v230, v228
	global_store_dword v227, v231, s[24:25] offset:256
	v_mov_b32_dpp v232, v148 quad_perm:[1,0,3,2] row_mask:0xf bank_mask:0xf
	s_nop 0
	v_perm_b32 v233, v148, v232, v228
	global_store_dword v227, v233, s[24:25] offset:288
	v_mov_b32_dpp v234, v140 quad_perm:[1,0,3,2] row_mask:0xf bank_mask:0xf
	s_nop 0
	v_perm_b32 v235, v140, v234, v228
	global_store_dword v227, v235, s[24:25] offset:320
	v_mov_b32_dpp v236, v132 quad_perm:[1,0,3,2] row_mask:0xf bank_mask:0xf
	s_nop 0
	v_perm_b32 v237, v132, v236, v228
	global_store_dword v227, v237, s[24:25] offset:352
	s_add_u32 s24, s10, 0x10100
	s_addc_u32 s25, s11, 0
	v_mov_b32_dpp v230, v189 quad_perm:[1,0,3,2] row_mask:0xf bank_mask:0xf
	s_nop 0
	v_perm_b32 v231, v189, v230, v228
	global_store_dword v227, v231, s[24:25] offset:0
	v_mov_b32_dpp v232, v181 quad_perm:[1,0,3,2] row_mask:0xf bank_mask:0xf
	s_nop 0
	v_perm_b32 v233, v181, v232, v228
	global_store_dword v227, v233, s[24:25] offset:32
	v_mov_b32_dpp v234, v173 quad_perm:[1,0,3,2] row_mask:0xf bank_mask:0xf
	s_nop 0
	v_perm_b32 v235, v173, v234, v228
	global_store_dword v227, v235, s[24:25] offset:64
	v_mov_b32_dpp v236, v165 quad_perm:[1,0,3,2] row_mask:0xf bank_mask:0xf
	s_nop 0
	v_perm_b32 v237, v165, v236, v228
	global_store_dword v227, v237, s[24:25] offset:96
	v_mov_b32_dpp v230, v157 quad_perm:[1,0,3,2] row_mask:0xf bank_mask:0xf
	s_nop 0
	v_perm_b32 v231, v157, v230, v228
	global_store_dword v227, v231, s[24:25] offset:256
	v_mov_b32_dpp v232, v149 quad_perm:[1,0,3,2] row_mask:0xf bank_mask:0xf
	s_nop 0
	v_perm_b32 v233, v149, v232, v228
	global_store_dword v227, v233, s[24:25] offset:288
	v_mov_b32_dpp v234, v141 quad_perm:[1,0,3,2] row_mask:0xf bank_mask:0xf
	s_nop 0
	v_perm_b32 v235, v141, v234, v228
	global_store_dword v227, v235, s[24:25] offset:320
	v_mov_b32_dpp v236, v133 quad_perm:[1,0,3,2] row_mask:0xf bank_mask:0xf
	s_nop 0
	v_perm_b32 v237, v133, v236, v228
	global_store_dword v227, v237, s[24:25] offset:352
	s_add_u32 s24, s10, 0x20200
	s_addc_u32 s25, s11, 0
	v_mov_b32_dpp v230, v190 quad_perm:[1,0,3,2] row_mask:0xf bank_mask:0xf
	s_nop 0
	v_perm_b32 v231, v190, v230, v228
	global_store_dword v227, v231, s[24:25] offset:0
	v_mov_b32_dpp v232, v182 quad_perm:[1,0,3,2] row_mask:0xf bank_mask:0xf
	s_nop 0
	v_perm_b32 v233, v182, v232, v228
	global_store_dword v227, v233, s[24:25] offset:32
	v_mov_b32_dpp v234, v174 quad_perm:[1,0,3,2] row_mask:0xf bank_mask:0xf
	s_nop 0
	v_perm_b32 v235, v174, v234, v228
	global_store_dword v227, v235, s[24:25] offset:64
	v_mov_b32_dpp v236, v166 quad_perm:[1,0,3,2] row_mask:0xf bank_mask:0xf
	s_nop 0
	v_perm_b32 v237, v166, v236, v228
	global_store_dword v227, v237, s[24:25] offset:96
	v_mov_b32_dpp v230, v158 quad_perm:[1,0,3,2] row_mask:0xf bank_mask:0xf
	s_nop 0
	v_perm_b32 v231, v158, v230, v228
	global_store_dword v227, v231, s[24:25] offset:256
	v_mov_b32_dpp v232, v150 quad_perm:[1,0,3,2] row_mask:0xf bank_mask:0xf
	s_nop 0
	v_perm_b32 v233, v150, v232, v228
	global_store_dword v227, v233, s[24:25] offset:288
	v_mov_b32_dpp v234, v142 quad_perm:[1,0,3,2] row_mask:0xf bank_mask:0xf
	s_nop 0
	v_perm_b32 v235, v142, v234, v228
	global_store_dword v227, v235, s[24:25] offset:320
	v_mov_b32_dpp v236, v134 quad_perm:[1,0,3,2] row_mask:0xf bank_mask:0xf
	s_nop 0
	v_perm_b32 v237, v134, v236, v228
	global_store_dword v227, v237, s[24:25] offset:352
	s_add_u32 s24, s10, 0x30300
	s_addc_u32 s25, s11, 0
	v_mov_b32_dpp v230, v191 quad_perm:[1,0,3,2] row_mask:0xf bank_mask:0xf
	s_nop 0
	v_perm_b32 v231, v191, v230, v228
	global_store_dword v227, v231, s[24:25] offset:0
	v_mov_b32_dpp v232, v183 quad_perm:[1,0,3,2] row_mask:0xf bank_mask:0xf
	s_nop 0
	v_perm_b32 v233, v183, v232, v228
	global_store_dword v227, v233, s[24:25] offset:32
	v_mov_b32_dpp v234, v175 quad_perm:[1,0,3,2] row_mask:0xf bank_mask:0xf
	s_nop 0
	v_perm_b32 v235, v175, v234, v228
	global_store_dword v227, v235, s[24:25] offset:64
	v_mov_b32_dpp v236, v167 quad_perm:[1,0,3,2] row_mask:0xf bank_mask:0xf
	s_nop 0
	v_perm_b32 v237, v167, v236, v228
	global_store_dword v227, v237, s[24:25] offset:96
	v_mov_b32_dpp v230, v159 quad_perm:[1,0,3,2] row_mask:0xf bank_mask:0xf
	s_nop 0
; __device__ __forceinline__ unsigned cvt_pk_bf16(float lo, float hi) { return pk_bf16(lo, hi); }
;     __device__ __forceinline__ void operator()(const f32x4 (&acc)[2][2][4][2], const Unit& u, int wr, int wc, int fr, int fq) const {
;     ...
;             EPI_ROWS_BEGIN
;                 const int cc = (pn - 8) * 256 + colt, vh = cc >> 6, d = cc & 63, b = row >> 14, t = row & (SEQ - 1);
;                 bf16_t* dst = vt + ((size_t)(b * 12 + vh) * 64 + d) * VTP + t;
;                 const unsigned w0 = cvt_pk_bf16(v0[0], v0[1]), w1 = cvt_pk_bf16(v0[2], v0[3]), w2 = cvt_pk_bf16(v1[0], v1[1]), w3 = cvt_pk_bf16(v1[2], v1[3]);
;                 dst[0 * (size_t)VTP] = (bf16_t)(w0 & 0xffffu); dst[1 * (size_t)VTP] = (bf16_t)(w0 >> 16);
;                 dst[2 * (size_t)VTP] = (bf16_t)(w1 & 0xffffu); dst[3 * (size_t)VTP] = (bf16_t)(w1 >> 16);
;                 dst[4 * (size_t)VTP] = (bf16_t)(w2 & 0xffffu); dst[5 * (size_t)VTP] = (bf16_t)(w2 >> 16);
;                 dst[6 * (size_t)VTP] = (bf16_t)(w3 & 0xffffu); dst[7 * (size_t)VTP] = (bf16_t)(w3 >> 16);
;             EPI_ROWS_END
	v_perm_b32 v231, v159, v230, v228
	global_store_dword v227, v231, s[24:25] offset:256
	v_mov_b32_dpp v232, v151 quad_perm:[1,0,3,2] row_mask:0xf bank_mask:0xf
	s_nop 0
	v_perm_b32 v233, v151, v232, v228
	global_store_dword v227, v233, s[24:25] offset:288
	v_mov_b32_dpp v234, v143 quad_perm:[1,0,3,2] row_mask:0xf bank_mask:0xf
	s_nop 0
	v_perm_b32 v235, v143, v234, v228
	global_store_dword v227, v235, s[24:25] offset:320
	v_mov_b32_dpp v236, v135 quad_perm:[1,0,3,2] row_mask:0xf bank_mask:0xf
	s_nop 0
	v_perm_b32 v237, v135, v236, v228
	global_store_dword v227, v237, s[24:25] offset:352
	s_add_u32 s24, s10, 0x404000
	s_addc_u32 s25, s11, 0
	v_mov_b32_dpp v230, v184 quad_perm:[1,0,3,2] row_mask:0xf bank_mask:0xf
	s_nop 0
	v_perm_b32 v231, v184, v230, v228
	global_store_dword v227, v231, s[24:25] offset:0
	v_mov_b32_dpp v232, v176 quad_perm:[1,0,3,2] row_mask:0xf bank_mask:0xf
	s_nop 0
	v_perm_b32 v233, v176, v232, v228
	global_store_dword v227, v233, s[24:25] offset:32
	v_mov_b32_dpp v234, v168 quad_perm:[1,0,3,2] row_mask:0xf bank_mask:0xf
	s_nop 0
	v_perm_b32 v235, v168, v234, v228
	global_store_dword v227, v235, s[24:25] offset:64
	v_mov_b32_dpp v236, v160 quad_perm:[1,0,3,2] row_mask:0xf bank_mask:0xf
	s_nop 0
	v_perm_b32 v237, v160, v236, v228
	global_store_dword v227, v237, s[24:25] offset:96
	v_mov_b32_dpp v230, v152 quad_perm:[1,0,3,2] row_mask:0xf bank_mask:0xf
	s_nop 0
	v_perm_b32 v231, v152, v230, v228
	global_store_dword v227, v231, s[24:25] offset:256
	v_mov_b32_dpp v232, v144 quad_perm:[1,0,3,2] row_mask:0xf bank_mask:0xf
	s_nop 0
	v_perm_b32 v233, v144, v232, v228
	global_store_dword v227, v233, s[24:25] offset:288
	v_mov_b32_dpp v234, v136 quad_perm:[1,0,3,2] row_mask:0xf bank_mask:0xf
	s_nop 0
	v_perm_b32 v235, v136, v234, v228
	global_store_dword v227, v235, s[24:25] offset:320
	v_mov_b32_dpp v236, v128 quad_perm:[1,0,3,2] row_mask:0xf bank_mask:0xf
	s_nop 0
	v_perm_b32 v237, v128, v236, v228
	global_store_dword v227, v237, s[24:25] offset:352
	s_add_u32 s24, s10, 0x414100
	s_addc_u32 s25, s11, 0
	v_mov_b32_dpp v230, v185 quad_perm:[1,0,3,2] row_mask:0xf bank_mask:0xf
	s_nop 0
	v_perm_b32 v231, v185, v230, v228
	global_store_dword v227, v231, s[24:25] offset:0
	v_mov_b32_dpp v232, v177 quad_perm:[1,0,3,2] row_mask:0xf bank_mask:0xf
	s_nop 0
	v_perm_b32 v233, v177, v232, v228
	global_store_dword v227, v233, s[24:25] offset:32
	v_mov_b32_dpp v234, v169 quad_perm:[1,0,3,2] row_mask:0xf bank_mask:0xf
	s_nop 0
	v_perm_b32 v235, v169, v234, v228
	global_store_dword v227, v235, s[24:25] offset:64
	v_mov_b32_dpp v236, v161 quad_perm:[1,0,3,2] row_mask:0xf bank_mask:0xf
	s_nop 0
	v_perm_b32 v237, v161, v236, v228
	global_store_dword v227, v237, s[24:25] offset:96
	v_mov_b32_dpp v230, v153 quad_perm:[1,0,3,2] row_mask:0xf bank_mask:0xf
	s_nop 0
	v_perm_b32 v231, v153, v230, v228
	global_store_dword v227, v231, s[24:25] offset:256
	v_mov_b32_dpp v232, v145 quad_perm:[1,0,3,2] row_mask:0xf bank_mask:0xf
	s_nop 0
	v_perm_b32 v233, v145, v232, v228
	global_store_dword v227, v233, s[24:25] offset:288
	v_mov_b32_dpp v234, v137 quad_perm:[1,0,3,2] row_mask:0xf bank_mask:0xf
	s_nop 0
	v_perm_b32 v235, v137, v234, v228
	global_store_dword v227, v235, s[24:25] offset:320
	v_mov_b32_dpp v236, v129 quad_perm:[1,0,3,2] row_mask:0xf bank_mask:0xf
	s_nop 0
	v_perm_b32 v237, v129, v236, v228
	global_store_dword v227, v237, s[24:25] offset:352
	s_add_u32 s24, s10, 0x424200
	s_addc_u32 s25, s11, 0
	v_mov_b32_dpp v230, v186 quad_perm:[1,0,3,2] row_mask:0xf bank_mask:0xf
	s_nop 0
	v_perm_b32 v231, v186, v230, v228
	global_store_dword v227, v231, s[24:25] offset:0
	v_mov_b32_dpp v232, v178 quad_perm:[1,0,3,2] row_mask:0xf bank_mask:0xf
	s_nop 0
	v_perm_b32 v233, v178, v232, v228
	global_store_dword v227, v233, s[24:25] offset:32
	v_mov_b32_dpp v234, v170 quad_perm:[1,0,3,2] row_mask:0xf bank_mask:0xf
	s_nop 0
	v_perm_b32 v235, v170, v234, v228
	global_store_dword v227, v235, s[24:25] offset:64
	v_mov_b32_dpp v236, v162 quad_perm:[1,0,3,2] row_mask:0xf bank_mask:0xf
	s_nop 0
	v_perm_b32 v237, v162, v236, v228
	global_store_dword v227, v237, s[24:25] offset:96
	v_mov_b32_dpp v230, v154 quad_perm:[1,0,3,2] row_mask:0xf bank_mask:0xf
	s_nop 0
	v_perm_b32 v231, v154, v230, v228
	global_store_dword v227, v231, s[24:25] offset:256
	v_mov_b32_dpp v232, v146 quad_perm:[1,0,3,2] row_mask:0xf bank_mask:0xf
	s_nop 0
	v_perm_b32 v233, v146, v232, v228
	global_store_dword v227, v233, s[24:25] offset:288
	v_mov_b32_dpp v234, v138 quad_perm:[1,0,3,2] row_mask:0xf bank_mask:0xf
	s_nop 0
	v_perm_b32 v235, v138, v234, v228
	global_store_dword v227, v235, s[24:25] offset:320
	v_mov_b32_dpp v236, v130 quad_perm:[1,0,3,2] row_mask:0xf bank_mask:0xf
	s_nop 0
	v_perm_b32 v237, v130, v236, v228
	global_store_dword v227, v237, s[24:25] offset:352
	s_add_u32 s24, s10, 0x434300
	s_addc_u32 s25, s11, 0
	v_mov_b32_dpp v230, v187 quad_perm:[1,0,3,2] row_mask:0xf bank_mask:0xf
	s_nop 0
	v_perm_b32 v231, v187, v230, v228
	global_store_dword v227, v231, s[24:25] offset:0
	v_mov_b32_dpp v232, v179 quad_perm:[1,0,3,2] row_mask:0xf bank_mask:0xf
	s_nop 0
	v_perm_b32 v233, v179, v232, v228
	global_store_dword v227, v233, s[24:25] offset:32
	v_mov_b32_dpp v234, v171 quad_perm:[1,0,3,2] row_mask:0xf bank_mask:0xf
	s_nop 0
	v_perm_b32 v235, v171, v234, v228
	global_store_dword v227, v235, s[24:25] offset:64
	v_mov_b32_dpp v236, v163 quad_perm:[1,0,3,2] row_mask:0xf bank_mask:0xf
	s_nop 0
	v_perm_b32 v237, v163, v236, v228
	global_store_dword v227, v237, s[24:25] offset:96
	v_mov_b32_dpp v230, v155 quad_perm:[1,0,3,2] row_mask:0xf bank_mask:0xf
	s_nop 0
	v_perm_b32 v231, v155, v230, v228
	global_store_dword v227, v231, s[24:25] offset:256
	v_mov_b32_dpp v232, v147 quad_perm:[1,0,3,2] row_mask:0xf bank_mask:0xf
	s_nop 0
	v_perm_b32 v233, v147, v232, v228
	global_store_dword v227, v233, s[24:25] offset:288
	v_mov_b32_dpp v234, v139 quad_perm:[1,0,3,2] row_mask:0xf bank_mask:0xf
	s_nop 0
	v_perm_b32 v235, v139, v234, v228
	global_store_dword v227, v235, s[24:25] offset:320
	v_mov_b32_dpp v236, v131 quad_perm:[1,0,3,2] row_mask:0xf bank_mask:0xf
	s_nop 0
	v_perm_b32 v237, v131, v236, v228
	global_store_dword v227, v237, s[24:25] offset:352
